# sample_proj: the four partial-sum LDS reads issued together with counted lgkmcnt waits (same summation order), plus the base/gate load hoist; on top of tail pulls 3/2
# baseline (speedup 1.0000x reference)
.LBB0_1476:
	s_or_b64 exec, exec, s[6:7]
	s_waitcnt lgkmcnt(0)
	s_barrier
	s_and_saveexec_b64 s[6:7], vcc
	s_cbranch_execz .LBB0_1473
	s_nop 0
	ds_read2st64_b32 v[2:3], v15 offset1:1
	ds_read2st64_b32 v[122:123], v15 offset0:2 offset1:3
	ds_read2st64_b32 v[124:125], v15 offset0:4 offset1:5
	ds_read2st64_b32 v[126:127], v15 offset0:6 offset1:7
	s_ashr_i32 s5, s4, 31
	s_waitcnt lgkmcnt(3)
	v_add_f32_e32 v2, 0, v2
	v_add_f32_e32 v4, v2, v3
	s_waitcnt lgkmcnt(2)
	v_add_f32_e32 v2, v4, v122
	v_add_f32_e32 v4, v2, v123
	s_waitcnt lgkmcnt(1)
	v_add_f32_e32 v2, v4, v124
	v_add_f32_e32 v4, v2, v125
	s_waitcnt lgkmcnt(0)
	v_add_f32_e32 v2, v4, v126
	v_add_f32_e32 v17, v2, v127
	v_lshl_add_u64 v[2:3], v[10:11], 0, s[4:5]
	v_lshlrev_b64 v[2:3], 2, v[2:3]
	v_lshl_add_u64 v[4:5], s[72:73], 0, v[2:3]
	v_mov_b32_e32 v18, v120
	v_lshl_add_u64 v[4:5], s[4:5], 2, v[12:13]
	v_mov_b32_e32 v4, v121
	v_lshl_add_u64 v[2:3], s[80:81], 0, v[2:3]
	s_waitcnt vmcnt(0)
	v_fmac_f32_e32 v18, v17, v4
	global_store_dword v[2:3], v18, off
	s_branch .LBB0_1473

.LBB0_1745:
	s_or_b64 exec, exec, s[10:11]
	s_waitcnt lgkmcnt(0)
	s_barrier
	s_and_saveexec_b64 s[10:11], vcc
	s_cbranch_execz .LBB0_1742
	s_nop 0
	ds_read2st64_b32 v[2:3], v15 offset1:1
	ds_read2st64_b32 v[122:123], v15 offset0:2 offset1:3
	ds_read2st64_b32 v[124:125], v15 offset0:4 offset1:5
	ds_read2st64_b32 v[126:127], v15 offset0:6 offset1:7
	s_ashr_i32 s9, s8, 31
	s_waitcnt lgkmcnt(3)
	v_add_f32_e32 v2, 0, v2
	v_add_f32_e32 v4, v2, v3
	s_waitcnt lgkmcnt(2)
	v_add_f32_e32 v2, v4, v122
	v_add_f32_e32 v4, v2, v123
	s_waitcnt lgkmcnt(1)
	v_add_f32_e32 v2, v4, v124
	v_add_f32_e32 v4, v2, v125
	s_waitcnt lgkmcnt(0)
	v_add_f32_e32 v2, v4, v126
	v_add_f32_e32 v17, v2, v127
	v_lshl_add_u64 v[2:3], v[10:11], 0, s[8:9]
	v_lshlrev_b64 v[2:3], 2, v[2:3]
	v_lshl_add_u64 v[4:5], s[80:81], 0, v[2:3]
	v_mov_b32_e32 v18, v120
	v_lshl_add_u64 v[4:5], s[8:9], 2, v[12:13]
	v_mov_b32_e32 v4, v121
	v_lshl_add_u64 v[2:3], s[4:5], 0, v[2:3]
	s_waitcnt vmcnt(0)
	v_fmac_f32_e32 v18, v17, v4
	global_store_dword v[2:3], v18, off
	s_branch .LBB0_1742
